# attention: fused softmax+PV (exps/adds/cvts in MFMA gaps), shorter post-S hazard pad, branch chain shortened, permlane only on rescale path, scalar-only active test
# speedup vs baseline: 1.0496x; 1.0109x over previous
; #define LAS __attribute__((address_space(3)))
; __device__ __forceinline__ float half_max(float v) { const unsigned u = __builtin_bit_cast(unsigned, v); auto rr = __builtin_amdgcn_permlane32_swap(u, u, false, false); return fmaxf(__builtin_bit_cast(float, (unsigned)rr[0]), __builtin_bit_cast(float, (unsigned)rr[1])); }
; template <bool DIFF> ...
;     ...
;         const bool active = split ? ((t % NG) == grp) : (t <= my_lim);
;         if (active) {
;             const LAS unsigned char* kbuf = lds + A_KB + k3 * 17408 + mp * 128;
;             const float cin = first ? 0.f : -m_;
;             f32x16 s0, s1;
; #pragma unroll
;             for (int ii = 0; ii < 16; ++ii) { s0[ii] = cin; s1[ii] = cin; }
; #pragma unroll
;             for (int ks = 0; ks < KS; ++ks) {
;                 const bf16x8 a0 = *(const LAS bf16x8*)(kbuf + r * 272 + (ks * 16 + h * 8) * 2);
;                 const bf16x8 a1 = *(const LAS bf16x8*)(kbuf + (32 + r) * 272 + (ks * 16 + h * 8) * 2);
;                 s0 = MFMA32(a0, bq[ks], s0); s1 = MFMA32(a1, bq[ks], s1);
;             }
;             if (t * 64 + 64 > nkeys) {
; #pragma unroll
;                 for (int ii = 0; ii < 16; ++ii) { const int key = t * 64 + crow(ii, h); if (key >= nkeys) s0[ii] = -INFINITY; if (key + 32 >= nkeys) s1[ii] = -INFINITY; }
;             }
;             asm volatile("s_nop 15\n\ts_nop 7" : "+v"(s0), "+v"(s1));
;             float mx;
;             {
;                 float a0 = max3f(s0[0], s0[1], s0[2]), a1 = max3f(s0[3], s0[4], s0[5]), a2 = max3f(s0[6], s0[7], s0[8]), a3 = max3f(s0[9], s0[10], s0[11]);
;                 float b0 = max3f(s1[0], s1[1], s1[2]), b1 = max3f(s1[3], s1[4], s1[5]), b2 = max3f(s1[6], s1[7], s1[8]), b3 = max3f(s1[9], s1[10], s1[11]);
;                 a0 = max3f(a0, s0[12], s0[13]); a1 = max3f(a1, s0[14], s0[15]); b0 = max3f(b0, s1[12], s1[13]); b1 = max3f(b1, s1[14], s1[15]);
;                 a0 = max3f(a0, a1, a2); b0 = max3f(b0, b1, b2); mx = max3f(a0, b0, a3); mx = max3f(mx, b3, b3);
;             }
;             mx = half_max(mx);
;             if (first || __any(mx > 6.0f)) {
;                 const float dl = first ? mx : ((mx > 6.0f) ? mx : 0.f);
;                 const float alpha = first ? 1.0f : __builtin_amdgcn_exp2f(-dl);
;                 m_ = first ? mx : m_ + dl; first = false;
.LBB0_1482:
	s_and_b32 s77, s15, 3
	s_cmp_eq_u32 s77, s88
	s_cselect_b32 s16, 1, 0
	s_cmp_le_i32 s15, s82
	s_cselect_b32 s17, 1, 0
	s_and_b64 s[78:79], exec, s[2:3]
	s_cselect_b32 s15, s16, s17
	s_bitcmp1_b32 s15, 0
	s_cselect_b64 s[78:79], -1, 0
	s_bitcmp0_b32 s15, 0
	s_cbranch_scc1 .LBB0_1493
	s_cmp_le_u32 s0, s1
	s_waitcnt lgkmcnt(0)
	v_mfma_f32_32x32x16_bf16 v[112:127], v[2:5], v[128:131], v[80:95]
	v_mfma_f32_32x32x16_bf16 v[96:111], v[10:13], v[128:131], v[80:95]
	v_mfma_f32_32x32x16_bf16 v[112:127], v[6:9], v[132:135], v[112:127]
	v_mfma_f32_32x32x16_bf16 v[96:111], v[212:215], v[132:135], v[96:111]
	v_mfma_f32_32x32x16_bf16 v[112:127], v[216:219], v[136:139], v[112:127]
	v_mfma_f32_32x32x16_bf16 v[96:111], v[224:227], v[136:139], v[96:111]
	v_mfma_f32_32x32x16_bf16 v[112:127], v[220:223], v[140:143], v[112:127]
	v_mfma_f32_32x32x16_bf16 v[96:111], v[228:231], v[140:143], v[96:111]
	s_cbranch_scc1 .LBB0_1485
	v_add_u32_e32 v0, s0, v177
	v_add_u32_e32 v2, 32, v0
	v_cmp_gt_u32_e32 vcc, s81, v2
	v_add_u32_e32 v2, 1, v0
	v_cmp_gt_u32_e64 s[44:45], s81, v2
	v_add_u32_e32 v2, 33, v0
	v_cmp_gt_u32_e64 s[14:15], s81, v2
	v_add_u32_e32 v2, 2, v0
	v_cmp_gt_u32_e64 s[48:49], s81, v2
	v_add_u32_e32 v2, 34, v0
	v_cmp_gt_u32_e64 s[16:17], s81, v2
	v_add_u32_e32 v2, 3, v0
	v_cmp_gt_u32_e64 s[50:51], s81, v2
	v_add_u32_e32 v2, 35, v0
	v_cmp_gt_u32_e64 s[18:19], s81, v2
	v_add_u32_e32 v2, 8, v0
	v_cmp_gt_u32_e64 s[52:53], s81, v2
	v_add_u32_e32 v2, 40, v0
	v_cmp_gt_u32_e64 s[20:21], s81, v2
	v_add_u32_e32 v2, 9, v0
	v_cmp_gt_u32_e64 s[54:55], s81, v2
	v_add_u32_e32 v2, 41, v0
	v_cmp_gt_u32_e64 s[22:23], s81, v2
	v_add_u32_e32 v2, 10, v0
	v_cmp_gt_u32_e64 s[56:57], s81, v2
	v_add_u32_e32 v2, 42, v0
	v_cmp_gt_u32_e64 s[24:25], s81, v2
	v_add_u32_e32 v2, 11, v0
	v_cmp_gt_u32_e64 s[58:59], s81, v2
	v_add_u32_e32 v2, 43, v0
	v_cmp_gt_u32_e64 s[26:27], s81, v2
	v_add_u32_e32 v2, 16, v0
	v_cmp_gt_u32_e64 s[60:61], s81, v2
	v_add_u32_e32 v2, 48, v0
	v_cmp_gt_u32_e64 s[28:29], s81, v2
	v_add_u32_e32 v2, 17, v0
	v_cmp_gt_u32_e64 s[62:63], s81, v2
	v_add_u32_e32 v2, 49, v0
	v_cmp_gt_u32_e64 s[30:31], s81, v2
	v_add_u32_e32 v2, 18, v0
	v_cmp_gt_u32_e64 s[64:65], s81, v2
	v_add_u32_e32 v2, 50, v0
	v_cmp_gt_u32_e64 s[34:35], s81, v2
	v_add_u32_e32 v2, 19, v0
	v_cmp_gt_u32_e64 s[66:67], s81, v2
	v_add_u32_e32 v2, 51, v0
	v_cmp_gt_u32_e64 s[36:37], s81, v2
	v_add_u32_e32 v2, 24, v0
	v_cmp_gt_u32_e64 s[68:69], s81, v2
	v_add_u32_e32 v2, 56, v0
	v_cmp_gt_u32_e64 s[38:39], s81, v2
	v_add_u32_e32 v2, 25, v0
	v_cmp_gt_u32_e64 s[70:71], s81, v2
	v_add_u32_e32 v2, 57, v0
	v_cmp_gt_u32_e64 s[42:43], s81, v2
	v_add_u32_e32 v2, 26, v0
	v_cmp_gt_u32_e64 s[72:73], s81, v2
	v_add_u32_e32 v2, 58, v0
	v_cmp_gt_u32_e64 s[46:47], s81, v2
	v_add_u32_e32 v2, 27, v0
	v_cmp_gt_u32_e64 s[74:75], s81, v2
	s_or_b64 s[72:73], s[74:75], s[72:73]
	s_or_b64 s[70:71], s[72:73], s[70:71]
	s_or_b64 s[68:69], s[70:71], s[68:69]
	s_or_b64 s[66:67], s[68:69], s[66:67]
	s_or_b64 s[64:65], s[66:67], s[64:65]
	s_or_b64 s[62:63], s[64:65], s[62:63]
	s_or_b64 s[60:61], s[62:63], s[60:61]
	s_or_b64 s[58:59], s[60:61], s[58:59]
	s_or_b64 s[56:57], s[58:59], s[56:57]
	s_or_b64 s[54:55], s[56:57], s[54:55]
	s_or_b64 s[52:53], s[54:55], s[52:53]
	s_or_b64 s[50:51], s[52:53], s[50:51]
	s_or_b64 s[48:49], s[50:51], s[48:49]
	v_cmp_gt_u32_e64 s[40:41], s81, v0
	s_or_b64 s[44:45], s[48:49], s[44:45]
	s_or_b64 s[40:41], s[44:45], s[40:41]
	v_add_u32_e32 v0, 59, v0
	v_cndmask_b32_e64 v112, v211, v112, s[40:41]
	v_cmp_gt_u32_e64 s[40:41], s81, v0
	v_cndmask_b32_e64 v127, v211, v127, s[74:75]
	v_cndmask_b32_e64 v126, v211, v126, s[72:73]
	v_cndmask_b32_e64 v111, v211, v111, s[40:41]
	s_or_b64 s[40:41], s[40:41], s[46:47]
	v_cndmask_b32_e64 v110, v211, v110, s[40:41]
	s_or_b64 s[40:41], s[40:41], s[42:43]
	s_or_b64 s[38:39], s[40:41], s[38:39]
	s_or_b64 s[36:37], s[38:39], s[36:37]
	s_or_b64 s[34:35], s[36:37], s[34:35]
	s_or_b64 s[30:31], s[34:35], s[30:31]
	s_or_b64 s[28:29], s[30:31], s[28:29]
	s_or_b64 s[26:27], s[28:29], s[26:27]
	s_or_b64 s[24:25], s[26:27], s[24:25]
	s_or_b64 s[22:23], s[24:25], s[22:23]
	s_or_b64 s[20:21], s[22:23], s[20:21]
	s_or_b64 s[18:19], s[20:21], s[18:19]
	s_or_b64 s[16:17], s[18:19], s[16:17]
	s_or_b64 s[14:15], s[16:17], s[14:15]
	s_or_b64 vcc, s[14:15], vcc
	v_cndmask_b32_e64 v125, v211, v125, s[70:71]
	v_cndmask_b32_e64 v124, v211, v124, s[68:69]
	v_cndmask_b32_e64 v123, v211, v123, s[66:67]
	v_cndmask_b32_e64 v122, v211, v122, s[64:65]
	v_cndmask_b32_e64 v121, v211, v121, s[62:63]
	v_cndmask_b32_e64 v120, v211, v120, s[60:61]
	v_cndmask_b32_e64 v119, v211, v119, s[58:59]
	v_cndmask_b32_e64 v118, v211, v118, s[56:57]
	v_cndmask_b32_e64 v117, v211, v117, s[54:55]
	v_cndmask_b32_e64 v116, v211, v116, s[52:53]
	v_cndmask_b32_e64 v115, v211, v115, s[50:51]
	v_cndmask_b32_e64 v114, v211, v114, s[48:49]
	v_cndmask_b32_e64 v113, v211, v113, s[44:45]
	v_cndmask_b32_e64 v109, v211, v109, s[40:41]
	v_cndmask_b32_e64 v108, v211, v108, s[38:39]
	v_cndmask_b32_e64 v107, v211, v107, s[36:37]
	v_cndmask_b32_e64 v106, v211, v106, s[34:35]
	v_cndmask_b32_e64 v105, v211, v105, s[30:31]
	v_cndmask_b32_e64 v104, v211, v104, s[28:29]
	v_cndmask_b32_e64 v103, v211, v103, s[26:27]
	v_cndmask_b32_e64 v102, v211, v102, s[24:25]
	v_cndmask_b32_e64 v101, v211, v101, s[22:23]
	v_cndmask_b32_e64 v100, v211, v100, s[20:21]
	v_cndmask_b32_e64 v99, v211, v99, s[18:19]
	v_cndmask_b32_e64 v98, v211, v98, s[16:17]
	v_cndmask_b32_e64 v97, v211, v97, s[14:15]
	v_cndmask_b32_e32 v96, v211, v96, vcc
.LBB0_1485:
	s_nop 11
	s_xor_b64 s[14:15], s[12:13], -1
	v_max3_f32 v0, v112, v113, v114
	v_max3_f32 v2, v115, v116, v117
	v_max3_f32 v3, v118, v119, v120
	v_max3_f32 v5, v96, v97, v98
	v_max3_f32 v6, v99, v100, v101
	v_max3_f32 v4, v121, v122, v123
	s_nop 0
	v_max3_f32 v0, v0, v124, v125
	v_max3_f32 v2, v2, v126, v127
	v_max3_f32 v7, v102, v103, v104
	v_max3_f32 v5, v5, v108, v109
	v_max3_f32 v6, v6, v110, v111
	v_max3_f32 v8, v105, v106, v107
	s_and_b64 vcc, exec, s[14:15]
	v_max3_f32 v0, v0, v2, v3
	v_max3_f32 v2, v5, v6, v7
	s_nop 0
	v_max3_f32 v0, v0, v2, v4
	s_nop 0
	v_max3_f32 v0, v0, v8, v8
	s_nop 0
	s_cbranch_vccz .Lattn_full
	s_mov_b32 s14, 0x40c00000
	v_cmp_lt_f32_e32 vcc, s14, v0
	s_cbranch_vccz .LBB0_1492
.Lattn_full:
	v_mov_b32_e32 v2, v0
	s_nop 1
	v_permlane32_swap_b32_e32 v0, v2
	v_max_f32_e32 v2, v0, v2
	s_xor_b64 s[14:15], s[12:13], -1
	s_and_b64 vcc, exec, s[14:15]
	s_cbranch_vccz .LBB0_1497
	s_mov_b32 s14, 0x40c00000
	v_cmp_lt_f32_e32 vcc, s14, v2
	s_mov_b64 s[16:17], 0
	s_mov_b64 s[14:15], 0
	s_cbranch_vccz .LBB0_1492
	v_cndmask_b32_e32 v0, 0, v2, vcc
	s_mov_b64 s[14:15], -1

; template <bool DIFF> ...
;     ...
; #pragma unroll
;             for (int ii = 0; ii < 16; ++ii) { s0[ii] = __builtin_amdgcn_exp2f(s0[ii]); s1[ii] = __builtin_amdgcn_exp2f(s1[ii]); }
;             pk[0][0] = pack8(s0, 0); pk[0][1] = pack8(s0, 8); pk[1][0] = pack8(s1, 0); pk[1][1] = pack8(s1, 8);
;         }
;         if (!late && active) A_PV(t & 3);
.LBB0_1492:
	s_mulk_i32 s77, 0x5000
	v_add_u32_e32 v0, s77, v205
	ds_read_b64_tr_b16 v[212:213], v0 offset:52224
	ds_read_b64_tr_b16 v[214:215], v0 offset:54784
	ds_read_b64_tr_b16 v[216:217], v0 offset:52288
	ds_read_b64_tr_b16 v[218:219], v0 offset:54848
	ds_read_b64_tr_b16 v[220:221], v0 offset:52352
	ds_read_b64_tr_b16 v[222:223], v0 offset:54912
	ds_read_b64_tr_b16 v[224:225], v0 offset:52416
	ds_read_b64_tr_b16 v[226:227], v0 offset:54976
	v_exp_f32_e32 v112, v112
	v_exp_f32_e32 v113, v113
	v_exp_f32_e32 v114, v114
	v_exp_f32_e32 v115, v115
	v_exp_f32_e32 v116, v116
	v_exp_f32_e32 v117, v117
	v_exp_f32_e32 v118, v118
	v_exp_f32_e32 v119, v119
	v_exp_f32_e32 v120, v120
	v_exp_f32_e32 v121, v121
	v_exp_f32_e32 v122, v122
	v_exp_f32_e32 v123, v123
	v_exp_f32_e32 v124, v124
	v_exp_f32_e32 v125, v125
	v_exp_f32_e32 v126, v126
	v_exp_f32_e32 v127, v127
	s_waitcnt lgkmcnt(4)
	ds_read_b64_tr_b16 v[228:229], v0 offset:57344
	ds_read_b64_tr_b16 v[230:231], v0 offset:59904
	ds_read_b64_tr_b16 v[232:233], v0 offset:57408
	ds_read_b64_tr_b16 v[234:235], v0 offset:59968
	ds_read_b64_tr_b16 v[236:237], v0 offset:57472
	ds_read_b64_tr_b16 v[238:239], v0 offset:60032
	ds_read_b64_tr_b16 v[244:245], v0 offset:57536
	ds_read_b64_tr_b16 v[246:247], v0 offset:60096
	v_cvt_pk_bf16_f32 v2, v112, v113
	v_cvt_pk_bf16_f32 v3, v114, v115
	v_cvt_pk_bf16_f32 v4, v116, v117
	v_cvt_pk_bf16_f32 v5, v118, v119
	v_cvt_pk_bf16_f32 v6, v120, v121
	v_cvt_pk_bf16_f32 v7, v122, v123
	v_cvt_pk_bf16_f32 v8, v124, v125
	v_cvt_pk_bf16_f32 v9, v126, v127
	v_add_u32_e32 v14, 0xcc00, v0
	s_waitcnt lgkmcnt(8)
	v_mfma_f32_32x32x16_bf16 v[32:47], v[212:215], v[2:5], v[32:47]
	v_exp_f32_e32 v96, v96
	v_exp_f32_e32 v97, v97
	v_add_f32_e32 v240, v240, v112
	v_add_f32_e32 v241, v241, v113
	v_mfma_f32_32x32x16_bf16 v[16:31], v[216:219], v[2:5], v[16:31]
	v_exp_f32_e32 v98, v98
	v_exp_f32_e32 v99, v99
	v_add_f32_e32 v242, v242, v114
	v_add_f32_e32 v243, v243, v115
	v_mfma_f32_32x32x16_bf16 v[48:63], v[220:223], v[2:5], v[48:63]
	v_exp_f32_e32 v100, v100
	v_exp_f32_e32 v101, v101
	v_add_f32_e32 v240, v240, v116
	v_add_f32_e32 v241, v241, v117
	v_mfma_f32_32x32x16_bf16 v[64:79], v[224:227], v[2:5], v[64:79]
	v_exp_f32_e32 v102, v102
	v_exp_f32_e32 v103, v103
	v_add_f32_e32 v242, v242, v118
	v_add_f32_e32 v243, v243, v119
	s_waitcnt lgkmcnt(4)
	ds_read_b64_tr_b16 v[212:213], v0 offset:62464
	ds_read_b64_tr_b16 v[214:215], v0 offset:65024
	ds_read_b64_tr_b16 v[216:217], v0 offset:62528
	ds_read_b64_tr_b16 v[218:219], v0 offset:65088
	ds_read_b64_tr_b16 v[220:221], v0 offset:62592
	ds_read_b64_tr_b16 v[222:223], v0 offset:65152
	ds_read_b64_tr_b16 v[224:225], v0 offset:62656
	ds_read_b64_tr_b16 v[226:227], v0 offset:65216
	s_waitcnt lgkmcnt(8)
	v_mfma_f32_32x32x16_bf16 v[32:47], v[228:231], v[6:9], v[32:47]
	v_exp_f32_e32 v104, v104
	v_exp_f32_e32 v105, v105
	v_add_f32_e32 v240, v240, v120
	v_add_f32_e32 v241, v241, v121
	v_mfma_f32_32x32x16_bf16 v[16:31], v[232:235], v[6:9], v[16:31]
	v_exp_f32_e32 v106, v106
	v_exp_f32_e32 v107, v107
	v_add_f32_e32 v242, v242, v122
	v_add_f32_e32 v243, v243, v123
	v_mfma_f32_32x32x16_bf16 v[48:63], v[236:239], v[6:9], v[48:63]
	v_exp_f32_e32 v108, v108
	v_exp_f32_e32 v109, v109
	v_add_f32_e32 v240, v240, v124
	v_add_f32_e32 v241, v241, v125
	v_mfma_f32_32x32x16_bf16 v[64:79], v[244:247], v[6:9], v[64:79]
	v_exp_f32_e32 v110, v110
	v_exp_f32_e32 v111, v111
	v_add_f32_e32 v242, v242, v126
	v_add_f32_e32 v243, v243, v127
	v_cvt_pk_bf16_f32 v10, v96, v97
	v_cvt_pk_bf16_f32 v11, v98, v99
	v_cvt_pk_bf16_f32 v12, v100, v101
	v_cvt_pk_bf16_f32 v13, v102, v103
	s_waitcnt lgkmcnt(4)
	ds_read_b64_tr_b16 v[228:229], v14 offset:15360
	ds_read_b64_tr_b16 v[230:231], v14 offset:17920
	ds_read_b64_tr_b16 v[232:233], v14 offset:15424
	ds_read_b64_tr_b16 v[234:235], v14 offset:17984
	ds_read_b64_tr_b16 v[236:237], v14 offset:15488
	ds_read_b64_tr_b16 v[238:239], v14 offset:18048
	ds_read_b64_tr_b16 v[244:245], v14 offset:15552
	ds_read_b64_tr_b16 v[246:247], v14 offset:18112
	s_waitcnt lgkmcnt(8)
	v_mfma_f32_32x32x16_bf16 v[32:47], v[212:215], v[10:13], v[32:47]
	v_cvt_pk_bf16_f32 v248, v104, v105
	v_cvt_pk_bf16_f32 v249, v106, v107
	v_add_f32_e32 v240, v240, v96
	v_add_f32_e32 v241, v241, v97
	v_mfma_f32_32x32x16_bf16 v[16:31], v[216:219], v[10:13], v[16:31]
	v_cvt_pk_bf16_f32 v250, v108, v109
	v_cvt_pk_bf16_f32 v251, v110, v111
	v_add_f32_e32 v242, v242, v98
	v_add_f32_e32 v243, v243, v99
	v_mfma_f32_32x32x16_bf16 v[48:63], v[220:223], v[10:13], v[48:63]
	v_add_f32_e32 v240, v240, v100
	v_add_f32_e32 v241, v241, v101
	v_add_f32_e32 v242, v242, v102
	v_add_f32_e32 v243, v243, v103
	v_mfma_f32_32x32x16_bf16 v[64:79], v[224:227], v[10:13], v[64:79]
	v_add_f32_e32 v240, v240, v104
	v_add_f32_e32 v241, v241, v105
	v_add_f32_e32 v242, v242, v106
	v_add_f32_e32 v243, v243, v107
	s_waitcnt lgkmcnt(0)
	v_mfma_f32_32x32x16_bf16 v[32:47], v[228:231], v[248:251], v[32:47]
	v_add_f32_e32 v240, v240, v108
	v_add_f32_e32 v241, v241, v109
	v_mfma_f32_32x32x16_bf16 v[16:31], v[232:235], v[248:251], v[16:31]
	v_add_f32_e32 v242, v242, v110
	v_add_f32_e32 v243, v243, v111
	v_mfma_f32_32x32x16_bf16 v[48:63], v[236:239], v[248:251], v[48:63]
	v_mfma_f32_32x32x16_bf16 v[64:79], v[244:247], v[248:251], v[64:79]
	s_mov_b64 s[12:13], 0
.LBB0_1493:
.LBB0_1495:
	s_waitcnt vmcnt(0) lgkmcnt(0)
	s_barrier
	s_add_i32 s0, s0, 64
	s_cmp_eq_u32 s80, s85
	s_cbranch_scc1 .LBB0_1498
	s_mov_b32 s14, s84
	s_mov_b32 s15, s85
	s_branch .LBB0_1480
